# static s_setprio 1 for waves 0-3 in the attention main loop, per-MFMA toggles removed (strategy 7.4, other half)
# baseline (speedup 1.0000x reference)
.LBB0_198:
	v_or_b32_e32 v0, s61, v98
	v_readlane_b32 s68, v254, 23
	v_ashrrev_i32_e32 v1, 31, v0
	v_readlane_b32 s80, v254, 35
	v_readlane_b32 s81, v254, 36
	s_lshr_b32 s15, s54, 2
	s_and_b32 s14, s15, s14
	v_lshl_add_u64 v[0:1], v[0:1], 2, s[80:81]
	global_load_dword v2, v[0:1], off
	s_and_b32 s15, s5, 1
	s_lshl_b32 s5, s16, 12
	s_lshl_b32 s18, s54, 6
	s_add_i32 s24, s5, 0x8000
	s_lshl_b32 s5, s15, 8
	s_and_b32 s18, s18, 0xc0
	s_or_b32 s5, s5, s18
	s_lshl_b32 s17, s16, 13
	s_lshl_b32 s18, s5, 1
	s_add_u32 s18, s58, s18
	s_addc_u32 s19, s59, 0
	s_lshl_b32 s15, s15, 7
	v_readlane_b32 s26, v255, 10
	v_readlane_b32 s27, v255, 11
	s_add_u32 s54, s26, s15
	s_addc_u32 s55, s27, 0
	v_readlane_b32 s26, v255, 6
	v_readlane_b32 s27, v255, 7
	s_add_u32 s56, s26, s15
	s_addc_u32 s57, s27, 0
	s_lshl_b32 s14, s14, 8
	s_cmp_lt_i32 s16, 8
	s_cselect_b32 s16, s17, s24
	v_ashrrev_i32_e32 v0, 1, v97
	s_movk_i32 s15, 0xffe0
	v_and_or_b32 v0, v0, s15, v195
	s_cselect_b32 s15, 0x7d, 61
	s_add_i32 s14, s16, s14
	v_add_u32_e32 v0, s14, v0
	v_ashrrev_i32_e32 v1, 31, v0
	v_lshlrev_b64 v[0:1], 10, v[0:1]
	v_lshl_add_u64 v[0:1], s[18:19], 0, v[0:1]
	v_lshlrev_b32_e32 v168, 4, v193
	v_lshl_add_u64 v[0:1], v[0:1], 0, v[168:169]
	global_load_dwordx4 v[120:123], v[0:1], off
	global_load_dwordx4 v[116:119], v[0:1], off offset:32
	global_load_dwordx4 v[112:115], v[0:1], off offset:64
	global_load_dwordx4 v[124:127], v[0:1], off offset:96
	v_and_b32_e32 v3, 64, v182
	s_waitcnt vmcnt(10)
	v_xor_b32_e32 v4, 32, v182
	v_add_u32_e32 v3, 64, v3
	v_cmp_lt_i32_e32 vcc, v4, v3
	v_xor_b32_e32 v5, 16, v182
	v_xor_b32_e32 v6, 8, v182
	v_cndmask_b32_e32 v4, v182, v4, vcc
	v_cmp_lt_i32_e32 vcc, v5, v3
	v_lshlrev_b32_e32 v168, 2, v4
	v_xor_b32_e32 v7, 4, v182
	v_cndmask_b32_e32 v5, v182, v5, vcc
	v_cmp_lt_i32_e32 vcc, v6, v3
	s_waitcnt vmcnt(8)
	v_xor_b32_e32 v8, 2, v182
	v_xor_b32_e32 v9, 1, v182
	v_cndmask_b32_e32 v6, v182, v6, vcc
	v_cmp_lt_i32_e32 vcc, v7, v3
	v_ashrrev_i32_e32 v10, 3, v97
	v_and_b32_e32 v11, 7, v97
	v_cndmask_b32_e32 v7, v182, v7, vcc
	v_cmp_lt_i32_e32 vcc, v8, v3
	v_lshlrev_b32_e32 v11, 4, v11
	v_lshlrev_b32_e32 v60, 7, v195
	v_cndmask_b32_e32 v0, v182, v8, vcc
	v_cmp_lt_i32_e32 vcc, v9, v3
	s_waitcnt vmcnt(6)
	v_lshlrev_b32_e32 v12, 2, v0
	v_lshlrev_b32_e32 v3, 2, v5
	v_cndmask_b32_e32 v1, v182, v9, vcc
	v_lshlrev_b32_e32 v13, 2, v1
	v_lshlrev_b32_e32 v8, 2, v6
	v_lshlrev_b32_e32 v9, 2, v7
	v_lshlrev_b32_e32 v64, 4, v97
	v_bfe_u32 v61, v97, 1, 3
	v_and_b32_e32 v200, 0xc0, v64
	v_mov_b32_e32 v197, 0
	s_mov_b32 s17, 0
	v_readlane_b32 s69, v254, 24
	v_readlane_b32 s70, v254, 25
	v_readlane_b32 s71, v254, 26
	v_readlane_b32 s72, v254, 27
	v_readlane_b32 s73, v254, 28
	v_readlane_b32 s74, v254, 29
	v_readlane_b32 s75, v254, 30
	s_waitcnt vmcnt(4)
	v_and_b32_e32 v4, 0x7fffffff, v2
	ds_bpermute_b32 v4, v168, v4
	v_max_f32_e64 v0, |v2|, |v2|
	v_readlane_b32 s76, v254, 31
	v_readlane_b32 s77, v254, 32
	v_readlane_b32 s78, v254, 33
	s_waitcnt lgkmcnt(0)
	v_max_f32_e32 v1, v4, v4
	v_max_f32_e32 v14, v0, v1
	v_add_u32_e32 v0, s16, v10
	v_lshl_or_b32 v198, v0, 8, v11
	ds_bpermute_b32 v15, v3, v14
	global_load_dwordx4 v[0:3], v198, s[54:55]
	global_load_dwordx4 v[4:7], v198, s[56:57]
	v_add_u32_e32 v204, 0x4000, v198
	global_load_dwordx4 v[48:51], v204, s[54:55]
	s_mov_b32 s16, 0xf800000
	s_waitcnt lgkmcnt(0)
	v_max_f32_e32 v11, v15, v15
	v_max_f32_e32 v11, v14, v11
	ds_bpermute_b32 v8, v8, v11
	v_readlane_b32 s79, v254, 34
	v_readlane_b32 s82, v254, 37
	v_readlane_b32 s83, v254, 38
	s_waitcnt lgkmcnt(0)
	v_max_f32_e32 v8, v8, v8
	v_max_f32_e32 v8, v11, v8
	ds_bpermute_b32 v9, v9, v8
	s_waitcnt lgkmcnt(0)
	v_max_f32_e32 v9, v9, v9
	v_max_f32_e32 v8, v8, v9
	ds_bpermute_b32 v9, v12, v8
	s_waitcnt vmcnt(6)
	v_and_b32_e32 v15, 0xffff0000, v120
	v_lshlrev_b32_e32 v14, 16, v120
	v_mul_f32_e32 v15, v15, v15
	v_lshlrev_b32_e32 v16, 16, v121
	v_fmac_f32_e32 v15, v14, v14
	v_and_b32_e32 v17, 0xffff0000, v121
	v_fmac_f32_e32 v15, v16, v16
	v_lshlrev_b32_e32 v18, 16, v122
	v_fmac_f32_e32 v15, v17, v17
	v_and_b32_e32 v19, 0xffff0000, v122
	v_fmac_f32_e32 v15, v18, v18
	v_lshlrev_b32_e32 v20, 16, v123
	v_fmac_f32_e32 v15, v19, v19
	v_and_b32_e32 v21, 0xffff0000, v123
	v_fmac_f32_e32 v15, v20, v20
	s_waitcnt vmcnt(5)
	v_lshlrev_b32_e32 v22, 16, v116
	v_fmac_f32_e32 v15, v21, v21
	v_and_b32_e32 v23, 0xffff0000, v116
	v_fmac_f32_e32 v15, v22, v22
	v_lshlrev_b32_e32 v24, 16, v117
	v_fmac_f32_e32 v15, v23, v23
	v_and_b32_e32 v25, 0xffff0000, v117
	v_fmac_f32_e32 v15, v24, v24
	v_lshlrev_b32_e32 v26, 16, v118
	v_fmac_f32_e32 v15, v25, v25
	v_and_b32_e32 v27, 0xffff0000, v118
	v_fmac_f32_e32 v15, v26, v26
	v_lshlrev_b32_e32 v28, 16, v119
	v_fmac_f32_e32 v15, v27, v27
	s_waitcnt lgkmcnt(0)
	v_max_f32_e32 v9, v9, v9
	v_fmac_f32_e32 v15, v28, v28
	v_max_f32_e32 v11, v8, v9
	v_and_b32_e32 v8, 0xffff0000, v119
	v_fmac_f32_e32 v15, v8, v8
	s_waitcnt vmcnt(4)
	v_lshlrev_b32_e32 v8, 16, v112
	v_fmac_f32_e32 v15, v8, v8
	v_and_b32_e32 v8, 0xffff0000, v112
	v_fmac_f32_e32 v15, v8, v8
	v_lshlrev_b32_e32 v8, 16, v113
	v_fmac_f32_e32 v15, v8, v8
	v_and_b32_e32 v8, 0xffff0000, v113
	v_fmac_f32_e32 v15, v8, v8
	v_lshlrev_b32_e32 v8, 16, v114
	v_fmac_f32_e32 v15, v8, v8
	v_and_b32_e32 v8, 0xffff0000, v114
	v_fmac_f32_e32 v15, v8, v8
	v_lshlrev_b32_e32 v8, 16, v115
	v_fmac_f32_e32 v15, v8, v8
	v_and_b32_e32 v8, 0xffff0000, v115
	v_fmac_f32_e32 v15, v8, v8
	s_waitcnt vmcnt(3)
	v_and_b32_e32 v9, 0xffff0000, v124
	v_lshlrev_b32_e32 v8, 16, v124
	v_pk_mul_f32 v[8:9], v[8:9], v[8:9]
	ds_bpermute_b32 v12, v13, v11
	v_add_f32_e32 v8, v8, v15
	v_add_f32_e32 v13, v9, v8
	v_and_b32_e32 v9, 0xffff0000, v125
	v_lshlrev_b32_e32 v8, 16, v125
	v_pk_mul_f32 v[8:9], v[8:9], v[8:9]
	v_lshrrev_b32_e32 v15, 1, v97
	v_add_f32_e32 v8, v8, v13
	v_add_f32_e32 v13, v9, v8
	v_and_b32_e32 v9, 0xffff0000, v126
	v_lshlrev_b32_e32 v8, 16, v126
	v_pk_mul_f32 v[8:9], v[8:9], v[8:9]
	v_bitop3_b32 v15, v193, v15, 7 bitop3:0x78
	v_add_f32_e32 v8, v8, v13
	v_add_f32_e32 v13, v9, v8
	v_and_b32_e32 v9, 0xffff0000, v127
	v_lshlrev_b32_e32 v8, 16, v127
	v_pk_mul_f32 v[8:9], v[8:9], v[8:9]
	v_lshl_or_b32 v201, v15, 4, v60
	v_add_f32_e32 v8, v8, v13
	v_add_f32_e32 v8, v9, v8
	ds_bpermute_b32 v9, v168, v8
	s_waitcnt lgkmcnt(1)
	v_max_f32_e32 v12, v12, v12
	v_max_f32_e32 v11, v11, v12
	v_lshlrev_b32_e32 v12, 10, v97
	v_and_b32_e32 v13, 48, v64
	s_waitcnt lgkmcnt(0)
	v_add_f32_e32 v8, v8, v9
	v_mul_f32_e32 v14, 0x4f800000, v8
	v_cmp_gt_f32_e32 vcc, s16, v8
	v_lshrrev_b32_e32 v9, 1, v10
	v_xor_b32_e32 v9, v9, v97
	v_cndmask_b32_e32 v8, v8, v14, vcc
	v_sqrt_f32_e32 v14, v8
	v_lshlrev_b32_e32 v9, 4, v9
	s_movk_i32 s16, 0x70
	v_and_b32_e32 v12, 0x1000, v12
	v_add_u32_e32 v15, -1, v14
	v_fma_f32 v16, -v15, v14, v8
	v_cmp_ge_f32_e64 s[42:43], 0, v16
	v_add_u32_e32 v16, 1, v14
	v_mul_f32_e32 v11, 0x41000000, v11
	v_cndmask_b32_e64 v15, v14, v15, s[42:43]
	v_fma_f32 v14, -v16, v14, v8
	v_cmp_lt_f32_e64 s[42:43], 0, v14
	v_mul_f32_e32 v11, 0xbf8147ae, v11
	s_nop 0
	v_cndmask_b32_e64 v14, v15, v16, s[42:43]
	v_mul_f32_e32 v15, 0x37800000, v14
	v_cndmask_b32_e32 v14, v14, v15, vcc
	v_cmp_class_f32_e32 vcc, v8, v173
	s_nop 1
	v_cndmask_b32_e32 v8, v14, v8, vcc
	v_lshlrev_b32_e32 v14, 7, v10
	v_and_or_b32 v202, v9, s16, v14
	s_waitcnt vmcnt(2)
	ds_write_b128 v202, v[0:3]
	v_lshl_or_b32 v0, v10, 6, v13
	v_add_u32_e32 v196, v0, v12
	s_waitcnt vmcnt(1)
	ds_write_b128 v196, v[4:7] offset:16384
	s_waitcnt lgkmcnt(0)
	s_barrier
	ds_read_b128 v[0:3], v201
	ds_read_b128 v[52:55], v201 offset:4096
	v_mul_f32_e32 v32, v11, v8
	v_mov_b32_e32 v33, v32
	v_mov_b32_e32 v34, v32
	v_mov_b32_e32 v35, v32
	v_mov_b32_e32 v36, v32
	v_mov_b32_e32 v37, v32
	v_mov_b32_e32 v38, v32
	v_mov_b32_e32 v39, v32
	v_mov_b32_e32 v40, v32
	v_mov_b32_e32 v41, v32
	v_mov_b32_e32 v42, v32
	v_mov_b32_e32 v43, v32
	v_mov_b32_e32 v44, v32
	v_mov_b32_e32 v45, v32
	v_mov_b32_e32 v46, v32
	v_mov_b32_e32 v47, v32
	s_mov_b32 s16, 0
	s_waitcnt lgkmcnt(1)
	v_mfma_f32_32x32x16_bf16 v[16:31], v[0:3], v[120:123], v[32:47]
	v_bitop3_b32 v0, v193, v61, 2 bitop3:0x36
	v_lshl_or_b32 v206, v0, 4, v60
	s_waitcnt lgkmcnt(0)
	v_mfma_f32_32x32x16_bf16 v[0:15], v[52:55], v[120:123], v[32:47]
	ds_read_b128 v[52:55], v206
	ds_read_b128 v[56:59], v206 offset:4096
	s_waitcnt lgkmcnt(1)
	v_mfma_f32_32x32x16_bf16 v[16:31], v[52:55], v[116:119], v[16:31]
	v_bitop3_b32 v52, v193, v61, 4 bitop3:0x36
	v_lshl_or_b32 v203, v52, 4, v60
	s_waitcnt lgkmcnt(0)
	v_mfma_f32_32x32x16_bf16 v[0:15], v[56:59], v[116:119], v[0:15]
	ds_read_b128 v[52:55], v203
	ds_read_b128 v[56:59], v203 offset:4096
	s_waitcnt lgkmcnt(1)
	v_mfma_f32_32x32x16_bf16 v[16:31], v[52:55], v[112:115], v[16:31]
	v_bitop3_b32 v52, v193, v61, 6 bitop3:0x36
	v_lshl_or_b32 v205, v52, 4, v60
	s_waitcnt lgkmcnt(0)
	v_mfma_f32_32x32x16_bf16 v[0:15], v[56:59], v[112:115], v[0:15]
	ds_read_b128 v[52:55], v205
	ds_read_b128 v[56:59], v205 offset:4096
	s_waitcnt vmcnt(0)
	ds_write_b128 v202, v[48:51] offset:8192
	s_waitcnt lgkmcnt(0)
	s_barrier
	v_mfma_f32_32x32x16_bf16 v[16:31], v[52:55], v[124:127], v[16:31]
	v_mfma_f32_32x32x16_bf16 v[0:15], v[56:59], v[124:127], v[0:15]
	s_nop 10
	v_exp_f32_e32 v48, v16
	v_exp_f32_e32 v49, v17
	v_exp_f32_e32 v50, v18
	v_exp_f32_e32 v51, v19
	v_exp_f32_e32 v52, v20
	v_exp_f32_e32 v53, v21
	v_exp_f32_e32 v54, v22
	v_exp_f32_e32 v55, v23
	v_exp_f32_e32 v56, v24
	v_exp_f32_e32 v57, v25
	v_exp_f32_e32 v58, v26
	v_exp_f32_e32 v59, v27
	v_exp_f32_e32 v60, v28
	v_exp_f32_e32 v61, v29
	v_exp_f32_e32 v62, v30
	v_exp_f32_e32 v63, v31
	v_exp_f32_e32 v162, v0
	v_exp_f32_e32 v164, v1
	v_exp_f32_e32 v165, v2
	v_exp_f32_e32 v163, v3
	v_exp_f32_e32 v156, v4
	v_exp_f32_e32 v160, v5
	v_exp_f32_e32 v161, v6
	v_exp_f32_e32 v157, v7
	v_exp_f32_e32 v136, v8
	v_exp_f32_e32 v140, v9
	v_exp_f32_e32 v141, v10
	v_exp_f32_e32 v137, v11
	v_exp_f32_e32 v128, v12
	v_exp_f32_e32 v132, v13
	v_exp_f32_e32 v133, v14
	v_exp_f32_e32 v129, v15
	v_and_b32_e32 v0, 16, v97
	v_lshlrev_b32_e32 v1, 2, v98
	v_and_or_b32 v0, v1, 12, v0
	v_lshlrev_b32_e32 v199, 1, v0
	v_lshl_or_b32 v0, v193, 8, v200
	v_add_u32_e32 v207, v199, v0
	v_mov_b32_e32 v16, 0
	v_mov_b32_e32 v17, v197
	v_mov_b32_e32 v18, v197
	v_mov_b32_e32 v19, v197
	v_mov_b32_e32 v20, v197
	v_mov_b32_e32 v21, v197
	v_mov_b32_e32 v22, v197
	v_mov_b32_e32 v23, v197
	v_mov_b32_e32 v24, v197
	v_mov_b32_e32 v25, v197
	v_mov_b32_e32 v26, v197
	v_mov_b32_e32 v27, v197
	v_mov_b32_e32 v28, v197
	v_mov_b32_e32 v29, v197
	v_mov_b32_e32 v30, v197
	v_mov_b32_e32 v31, v197
	v_mov_b32_e32 v0, 0
	v_mov_b32_e32 v1, v197
	v_mov_b32_e32 v2, v197
	v_mov_b32_e32 v3, v197
	v_mov_b32_e32 v4, v197
	v_mov_b32_e32 v5, v197
	v_mov_b32_e32 v6, v197
	v_mov_b32_e32 v7, v197
	v_mov_b32_e32 v8, v197
	v_mov_b32_e32 v9, v197
	v_mov_b32_e32 v10, v197
	v_mov_b32_e32 v11, v197
	v_mov_b32_e32 v12, v197
	v_mov_b32_e32 v13, v197
	v_mov_b32_e32 v14, v197
	v_mov_b32_e32 v15, v197
	v_cmp_lt_u32_e32 vcc, 0xff, v192
	s_nop 1
	s_cbranch_vccnz .Lfg_prio_skip
	s_setprio 1
